# P7 epilogue head: 28 register moves / zero-inits paired into 14 v_mov_b64
# speedup vs baseline: 1.0024x; 1.0019x over previous
.LBB0_688:
	s_mul_hi_i32 s0, s20, 0x3e0f83e1
	s_lshr_b32 s1, s0, 31
	s_ashr_i32 s0, s0, 3
	s_add_i32 s0, s0, s1
	s_mul_i32 s1, s0, 33
	s_sub_i32 s16, s20, s1
	s_mul_i32 s1, s16, 0xfe
	s_lshl_b32 s0, s0, 13
	s_min_i32 s41, s1, 0x1f00
	s_add_i32 s41, s41, s0
	v_add_u32_e32 v194, s41, v200
	v_lshl_or_b32 v192, s12, 7, v211
	s_add_u32 s98, s82, 0x2c00
	s_addc_u32 s99, s83, 0
	s_add_u32 s100, s82, 0x8400
	s_addc_u32 s101, s83, 0
	v_lshlrev_b32_e32 v222, 2, v192
	v_ashrrev_i32_e32 v193, 31, v192
	global_load_dwordx4 v[120:123], v222, s[82:83]
	global_load_dwordx4 v[124:127], v222, s[98:99]
	global_load_dwordx4 v[128:131], v222, s[100:101]
	s_add_u32 s98, s82, 0xdc00
	s_addc_u32 s99, s83, 0
	global_load_dwordx4 v[132:135], v222, s[98:99]
	v_lshl_add_u64 v[196:197], v[192:193], 2, s[82:83]
	s_waitcnt vmcnt(10)
	v_mov_b64_e32 v[44:45], v[236:237]
	v_mov_b64_e32 v[46:47], v[238:239]
	v_mov_b64_e32 v[140:141], v[240:241]
	v_mov_b64_e32 v[142:143], v[242:243]
	v_mov_b64_e32 v[40:41], v[246:247]
	v_mov_b64_e32 v[42:43], v[248:249]
	v_mov_b64_e32 v[136:137], v[250:251]
	v_mov_b64_e32 v[138:139], v[252:253]
	v_mov_b32_e32 v198, v208
	v_mov_b32_e32 v221, v203
	v_mov_b32_e32 v220, v204
	v_mov_b32_e32 v219, v205
	v_mov_b32_e32 v218, v206
	v_mov_b32_e32 v199, v207
	v_fmamk_f32 v168, v244, 0x3a800000, v215
	v_rsq_f32_e32 v168, v168
	v_fmamk_f32 v169, v245, 0x3a800000, v215
	v_rsq_f32_e32 v170, v169
	v_pk_fma_f32 v[162:163], v[118:119], v[168:169], v[142:143] op_sel_hi:[1,0,1]
	v_pk_fma_f32 v[160:161], v[116:117], v[168:169], v[140:141] op_sel_hi:[1,0,1]
	v_pk_fma_f32 v[66:67], v[66:67], v[168:169], v[46:47] op_sel_hi:[1,0,1]
	v_pk_fma_f32 v[64:65], v[64:65], v[168:169], v[44:45] op_sel_hi:[1,0,1]
	v_pk_fma_f32 v[166:167], v[114:115], v[168:169], v[138:139] op_sel_hi:[1,0,1]
	v_pk_fma_f32 v[164:165], v[112:113], v[168:169], v[136:137] op_sel_hi:[1,0,1]
	s_add_u32 s98, s82, 0x5800
	s_addc_u32 s99, s83, 0
	s_add_u32 s100, s82, 0xb000
	s_addc_u32 s101, s83, 0
	global_load_dwordx4 v[112:115], v222, s[98:99]
	global_load_dwordx4 v[116:119], v222, s[100:101]
	v_pk_fma_f32 v[70:71], v[70:71], v[168:169], v[42:43] op_sel_hi:[1,0,1]
	v_pk_fma_f32 v[68:69], v[68:69], v[168:169], v[40:41] op_sel_hi:[1,0,1]
	v_pk_fma_f32 v[98:99], v[98:99], v[170:171], v[142:143] op_sel_hi:[1,0,1]
	v_pk_fma_f32 v[96:97], v[96:97], v[170:171], v[140:141] op_sel_hi:[1,0,1]
	v_pk_fma_f32 v[26:27], v[26:27], v[170:171], v[46:47] op_sel_hi:[1,0,1]
	v_pk_fma_f32 v[24:25], v[24:25], v[170:171], v[44:45] op_sel_hi:[1,0,1]
	v_pk_fma_f32 v[106:107], v[106:107], v[170:171], v[138:139] op_sel_hi:[1,0,1]
	v_pk_fma_f32 v[104:105], v[104:105], v[170:171], v[136:137] op_sel_hi:[1,0,1]
	v_pk_fma_f32 v[38:39], v[38:39], v[170:171], v[42:43] op_sel_hi:[1,0,1]
	v_pk_fma_f32 v[36:37], v[36:37], v[170:171], v[40:41] op_sel_hi:[1,0,1]
	s_and_saveexec_b64 s[0:1], s[4:5]
	s_cbranch_execz .LBB0_690
	ds_write_b128 v216, v[160:163]
	ds_write_b128 v216, v[64:67] offset:16
	ds_write_b128 v216, v[164:167] offset:32
	ds_write_b128 v216, v[68:71] offset:48
	ds_write_b128 v217, v[96:99]
	ds_write_b128 v217, v[24:27] offset:16
	ds_write_b128 v217, v[104:107] offset:32
	ds_write_b128 v217, v[36:39] offset:48
.LBB0_690:
	s_or_b64 exec, exec, s[0:1]
	s_waitcnt lgkmcnt(0)
	s_barrier
	v_cndmask_b32_e64 v168, 0, 1, s[34:35]
	v_mov_b32_e32 v232, 0
	v_add_u32_e32 v195, s63, v202
	v_cmp_ne_u32_e64 s[12:13], 1, v168
	s_andn2_b64 vcc, exec, s[34:35]
	v_mov_b32_e32 v235, 0
	v_mov_b32_e32 v238, 0
	v_mov_b32_e32 v241, 0
	v_mov_b64_e32 v[242:243], 0
	v_mov_b64_e32 v[244:245], 0
	v_mov_b64_e32 v[168:169], 0
	v_mov_b64_e32 v[170:171], 0
	v_mov_b64_e32 v[172:173], 0
	v_mov_b64_e32 v[174:175], 0
	s_cbranch_vccnz .LBB0_692
	ds_read_b128 v[168:171], v195 offset:256
	ds_read_b128 v[222:225], v195
	ds_read_b128 v[226:229], v195 offset:32
	ds_read_b128 v[172:175], v195 offset:288
	s_waitcnt lgkmcnt(2)
	v_cndmask_b32_e64 v232, v168, v222, s[6:7]
	v_cndmask_b32_e64 v235, v169, v223, s[6:7]
	v_cndmask_b32_e64 v238, v170, v224, s[6:7]
	v_cndmask_b32_e64 v241, v171, v225, s[6:7]
	s_waitcnt lgkmcnt(0)
	v_cndmask_b32_e64 v242, v172, v226, s[6:7]
	v_cndmask_b32_e64 v243, v173, v227, s[6:7]
	v_cndmask_b32_e64 v244, v174, v228, s[6:7]
	v_cndmask_b32_e64 v245, v175, v229, s[6:7]
